# all four GEMM K-loops (B, D, F, G): LDS-DMA pieces addressed as scalar base + 32-bit lane offset; two-term bases summed on the SALU
# baseline (speedup 1.0000x reference)
.LBB0_167:
	s_add_u32 s20, s66, 0xfff80080
	s_addc_u32 s21, s67, -1
	s_add_i32 s6, 0, 0x10000
	s_cmp_eq_u32 s25, 28
	s_cselect_b32 vcc_hi, s51, s21
	s_cselect_b32 vcc_lo, s53, s20
	s_cselect_b32 s69, s47, s24
	s_cselect_b32 s68, s12, s13
	s_add_i32 s7, 0, 0x14000
	v_add_u32_e32 v142, s6, v162
	v_add_u32_e32 v158, s7, v162
	ds_read_b128 v[130:133], v142
	ds_read_b128 v[134:137], v142 offset:1024
	ds_read_b128 v[138:141], v142 offset:2048
	ds_read_b128 v[142:145], v142 offset:3072
	ds_read_b128 v[168:171], v158
	ds_read_b128 v[172:175], v158 offset:1024
	ds_read_b128 v[176:179], v158 offset:2048
	ds_read_b128 v[180:183], v158 offset:3072
	s_add_i32 m0, s65, 0xc000
	ds_read_b128 v[184:187], v166
	ds_read_b128 v[188:191], v166 offset:1024
	ds_read_b128 v[200:203], v166 offset:2048
	ds_read_b128 v[204:207], v166 offset:3072
	ds_read_b128 v[214:217], v166 offset:4096
	ds_read_b128 v[218:221], v166 offset:5120
	ds_read_b128 v[222:225], v166 offset:6144
	ds_read_b128 v[226:229], v166 offset:7168
	global_load_lds_dwordx4 v154, s[66:67]
	s_add_i32 m0, s65, 0xe000
	s_nop 0
	global_load_lds_dwordx4 v156, s[66:67]
	s_waitcnt vmcnt(8)
	s_waitcnt lgkmcnt(0)
	s_barrier
	s_setprio 1
	s_waitcnt lgkmcnt(0)
	v_mfma_f32_16x16x32_bf16 v[126:129], v[130:133], v[184:187], v[126:129]
	v_mfma_f32_16x16x32_bf16 v[122:125], v[138:141], v[184:187], v[122:125]
	v_mfma_f32_16x16x32_bf16 v[110:113], v[130:133], v[200:203], v[110:113]
	v_mfma_f32_16x16x32_bf16 v[106:109], v[138:141], v[200:203], v[106:109]
	v_mfma_f32_16x16x32_bf16 v[94:97], v[130:133], v[214:217], v[94:97]
	v_mfma_f32_16x16x32_bf16 v[90:93], v[138:141], v[214:217], v[90:93]
	v_mfma_f32_16x16x32_bf16 v[78:81], v[130:133], v[222:225], v[78:81]
	v_mfma_f32_16x16x32_bf16 v[74:77], v[138:141], v[222:225], v[74:77]
	v_mfma_f32_16x16x32_bf16 v[126:129], v[134:137], v[188:191], v[126:129]
	v_mfma_f32_16x16x32_bf16 v[122:125], v[142:145], v[188:191], v[122:125]
	v_mfma_f32_16x16x32_bf16 v[110:113], v[134:137], v[204:207], v[110:113]
	v_mfma_f32_16x16x32_bf16 v[106:109], v[142:145], v[204:207], v[106:109]
	v_mfma_f32_16x16x32_bf16 v[94:97], v[134:137], v[218:221], v[94:97]
	v_mfma_f32_16x16x32_bf16 v[90:93], v[142:145], v[218:221], v[90:93]
	v_mfma_f32_16x16x32_bf16 v[78:81], v[134:137], v[226:229], v[78:81]
	v_mfma_f32_16x16x32_bf16 v[74:77], v[142:145], v[226:229], v[74:77]
	s_setprio 0
	s_setprio 1
	v_mfma_f32_16x16x32_bf16 v[118:121], v[168:171], v[184:187], v[118:121]
	v_mfma_f32_16x16x32_bf16 v[114:117], v[176:179], v[184:187], v[114:117]
	v_mfma_f32_16x16x32_bf16 v[102:105], v[168:171], v[200:203], v[102:105]
	v_mfma_f32_16x16x32_bf16 v[98:101], v[176:179], v[200:203], v[98:101]
	v_mfma_f32_16x16x32_bf16 v[86:89], v[168:171], v[214:217], v[86:89]
	v_mfma_f32_16x16x32_bf16 v[82:85], v[176:179], v[214:217], v[82:85]
	v_mfma_f32_16x16x32_bf16 v[70:73], v[168:171], v[222:225], v[70:73]
	v_mfma_f32_16x16x32_bf16 v[66:69], v[176:179], v[222:225], v[66:69]
	v_mfma_f32_16x16x32_bf16 v[118:121], v[172:175], v[188:191], v[118:121]
	v_mfma_f32_16x16x32_bf16 v[114:117], v[180:183], v[188:191], v[114:117]
	v_mfma_f32_16x16x32_bf16 v[102:105], v[172:175], v[204:207], v[102:105]
	v_mfma_f32_16x16x32_bf16 v[98:101], v[180:183], v[204:207], v[98:101]
	v_mfma_f32_16x16x32_bf16 v[86:89], v[172:175], v[218:221], v[86:89]
	v_mfma_f32_16x16x32_bf16 v[82:85], v[180:183], v[218:221], v[82:85]
	v_mfma_f32_16x16x32_bf16 v[70:73], v[172:175], v[226:229], v[70:73]
	v_mfma_f32_16x16x32_bf16 v[66:69], v[180:183], v[226:229], v[66:69]
	s_setprio 0
	s_barrier
	s_add_i32 s6, s6, s31
	s_mov_b32 m0, s6
	ds_read_b128 v[184:187], v166 offset:16384
	ds_read_b128 v[188:191], v166 offset:17408
	ds_read_b128 v[200:203], v166 offset:18432
	ds_read_b128 v[204:207], v166 offset:19456
	ds_read_b128 v[214:217], v166 offset:20480
	ds_read_b128 v[218:221], v166 offset:21504
	ds_read_b128 v[222:225], v166 offset:22528
	ds_read_b128 v[226:229], v166 offset:23552
	global_load_lds_dwordx4 v148, s[68:69]
	s_add_i32 m0, s6, 0x2000
	s_add_u32 s20, s68, 0x80000
	s_addc_u32 s21, s69, 0
	s_add_i32 s6, s7, s31
	global_load_lds_dwordx4 v152, s[68:69]
	s_mov_b32 m0, s6
	s_nop 0
	global_load_lds_dwordx4 v148, s[20:21]
	s_add_i32 m0, s6, 0x2000
	s_nop 0
	global_load_lds_dwordx4 v152, s[20:21]
	s_mov_b32 m0, s65
	s_nop 0
	global_load_lds_dwordx4 v146, vcc
	s_mov_b32 m0, s34
	s_nop 0
	global_load_lds_dwordx4 v150, vcc
	s_waitcnt vmcnt(8)
	s_waitcnt lgkmcnt(0)
	s_barrier
	s_setprio 1
	s_waitcnt lgkmcnt(0)
	v_mfma_f32_16x16x32_bf16 v[62:65], v[130:133], v[184:187], v[62:65]
	v_mfma_f32_16x16x32_bf16 v[58:61], v[138:141], v[184:187], v[58:61]
	v_mfma_f32_16x16x32_bf16 v[50:53], v[130:133], v[200:203], v[50:53]
	v_mfma_f32_16x16x32_bf16 v[42:45], v[138:141], v[200:203], v[42:45]
	v_mfma_f32_16x16x32_bf16 v[34:37], v[130:133], v[214:217], v[34:37]
	v_mfma_f32_16x16x32_bf16 v[26:29], v[138:141], v[214:217], v[26:29]
	v_mfma_f32_16x16x32_bf16 v[14:17], v[130:133], v[222:225], v[14:17]
	v_mfma_f32_16x16x32_bf16 v[10:13], v[138:141], v[222:225], v[10:13]
	v_mfma_f32_16x16x32_bf16 v[62:65], v[134:137], v[188:191], v[62:65]
	v_mfma_f32_16x16x32_bf16 v[58:61], v[142:145], v[188:191], v[58:61]
	v_mfma_f32_16x16x32_bf16 v[50:53], v[134:137], v[204:207], v[50:53]
	v_mfma_f32_16x16x32_bf16 v[42:45], v[142:145], v[204:207], v[42:45]
	v_mfma_f32_16x16x32_bf16 v[34:37], v[134:137], v[218:221], v[34:37]
	v_mfma_f32_16x16x32_bf16 v[26:29], v[142:145], v[218:221], v[26:29]
	v_mfma_f32_16x16x32_bf16 v[14:17], v[134:137], v[226:229], v[14:17]
	v_mfma_f32_16x16x32_bf16 v[10:13], v[142:145], v[226:229], v[10:13]
	s_setprio 0
	s_setprio 1
	v_mfma_f32_16x16x32_bf16 v[54:57], v[168:171], v[184:187], v[54:57]
	v_mfma_f32_16x16x32_bf16 v[46:49], v[176:179], v[184:187], v[46:49]
	v_mfma_f32_16x16x32_bf16 v[38:41], v[168:171], v[200:203], v[38:41]
	v_mfma_f32_16x16x32_bf16 v[30:33], v[176:179], v[200:203], v[30:33]
	v_mfma_f32_16x16x32_bf16 v[22:25], v[168:171], v[214:217], v[22:25]
	v_mfma_f32_16x16x32_bf16 v[18:21], v[176:179], v[214:217], v[18:21]
	v_mfma_f32_16x16x32_bf16 v[6:9], v[168:171], v[222:225], v[6:9]
	v_mfma_f32_16x16x32_bf16 v[2:5], v[176:179], v[222:225], v[2:5]
	v_mfma_f32_16x16x32_bf16 v[54:57], v[172:175], v[188:191], v[54:57]
	v_mfma_f32_16x16x32_bf16 v[46:49], v[180:183], v[188:191], v[46:49]
	v_mfma_f32_16x16x32_bf16 v[38:41], v[172:175], v[204:207], v[38:41]
	v_mfma_f32_16x16x32_bf16 v[30:33], v[180:183], v[204:207], v[30:33]
	v_mfma_f32_16x16x32_bf16 v[22:25], v[172:175], v[218:221], v[22:25]
	v_mfma_f32_16x16x32_bf16 v[18:21], v[180:183], v[218:221], v[18:21]
	v_mfma_f32_16x16x32_bf16 v[6:9], v[172:175], v[226:229], v[6:9]
	v_mfma_f32_16x16x32_bf16 v[2:5], v[180:183], v[226:229], v[2:5]
	s_setprio 0
	s_barrier
	s_add_i32 s6, 0, 0x18000
	s_add_i32 s7, 0, 0x1c000
	v_add_u32_e32 v142, s6, v162
	v_add_u32_e32 v167, s7, v162
	ds_read_b128 v[130:133], v142
	ds_read_b128 v[134:137], v142 offset:1024
	ds_read_b128 v[138:141], v142 offset:2048
	ds_read_b128 v[142:145], v142 offset:3072
	ds_read_b128 v[168:171], v167
	ds_read_b128 v[172:175], v167 offset:1024
	ds_read_b128 v[176:179], v167 offset:2048
	ds_read_b128 v[180:183], v167 offset:3072
	s_add_u32 s20, vcc_lo, 0x80000
	s_addc_u32 s21, vcc_hi, 0
	s_mov_b32 m0, s35
	ds_read_b128 v[184:187], v166 offset:32768
	ds_read_b128 v[188:191], v166 offset:33792
	ds_read_b128 v[200:203], v166 offset:34816
	ds_read_b128 v[204:207], v166 offset:35840
	ds_read_b128 v[214:217], v166 offset:36864
	ds_read_b128 v[218:221], v166 offset:37888
	ds_read_b128 v[222:225], v166 offset:38912
	ds_read_b128 v[226:229], v166 offset:39936
	global_load_lds_dwordx4 v146, s[20:21]
	s_mov_b32 m0, s36
	s_nop 0
	global_load_lds_dwordx4 v150, s[20:21]
	s_waitcnt vmcnt(8)
	s_waitcnt lgkmcnt(0)
	s_barrier
	s_setprio 1
	s_waitcnt lgkmcnt(0)
	v_mfma_f32_16x16x32_bf16 v[126:129], v[130:133], v[184:187], v[126:129]
	v_mfma_f32_16x16x32_bf16 v[122:125], v[138:141], v[184:187], v[122:125]
	v_mfma_f32_16x16x32_bf16 v[110:113], v[130:133], v[200:203], v[110:113]
	v_mfma_f32_16x16x32_bf16 v[106:109], v[138:141], v[200:203], v[106:109]
	v_mfma_f32_16x16x32_bf16 v[94:97], v[130:133], v[214:217], v[94:97]
	v_mfma_f32_16x16x32_bf16 v[90:93], v[138:141], v[214:217], v[90:93]
	v_mfma_f32_16x16x32_bf16 v[78:81], v[130:133], v[222:225], v[78:81]
	v_mfma_f32_16x16x32_bf16 v[74:77], v[138:141], v[222:225], v[74:77]
	v_mfma_f32_16x16x32_bf16 v[126:129], v[134:137], v[188:191], v[126:129]
	v_mfma_f32_16x16x32_bf16 v[122:125], v[142:145], v[188:191], v[122:125]
	v_mfma_f32_16x16x32_bf16 v[110:113], v[134:137], v[204:207], v[110:113]
	v_mfma_f32_16x16x32_bf16 v[106:109], v[142:145], v[204:207], v[106:109]
	v_mfma_f32_16x16x32_bf16 v[94:97], v[134:137], v[218:221], v[94:97]
	v_mfma_f32_16x16x32_bf16 v[90:93], v[142:145], v[218:221], v[90:93]
	v_mfma_f32_16x16x32_bf16 v[78:81], v[134:137], v[226:229], v[78:81]
	v_mfma_f32_16x16x32_bf16 v[74:77], v[142:145], v[226:229], v[74:77]
	s_setprio 0
	s_setprio 1
	v_mfma_f32_16x16x32_bf16 v[118:121], v[168:171], v[184:187], v[118:121]
	v_mfma_f32_16x16x32_bf16 v[114:117], v[176:179], v[184:187], v[114:117]
	v_mfma_f32_16x16x32_bf16 v[102:105], v[168:171], v[200:203], v[102:105]
	v_mfma_f32_16x16x32_bf16 v[98:101], v[176:179], v[200:203], v[98:101]
	v_mfma_f32_16x16x32_bf16 v[86:89], v[168:171], v[214:217], v[86:89]
	v_mfma_f32_16x16x32_bf16 v[82:85], v[176:179], v[214:217], v[82:85]
	v_mfma_f32_16x16x32_bf16 v[70:73], v[168:171], v[222:225], v[70:73]
	v_mfma_f32_16x16x32_bf16 v[66:69], v[176:179], v[222:225], v[66:69]
	v_mfma_f32_16x16x32_bf16 v[118:121], v[172:175], v[188:191], v[118:121]
	v_mfma_f32_16x16x32_bf16 v[114:117], v[180:183], v[188:191], v[114:117]
	v_mfma_f32_16x16x32_bf16 v[102:105], v[172:175], v[204:207], v[102:105]
	v_mfma_f32_16x16x32_bf16 v[98:101], v[180:183], v[204:207], v[98:101]
	v_mfma_f32_16x16x32_bf16 v[86:89], v[172:175], v[218:221], v[86:89]
	v_mfma_f32_16x16x32_bf16 v[82:85], v[180:183], v[218:221], v[82:85]
	v_mfma_f32_16x16x32_bf16 v[70:73], v[172:175], v[226:229], v[70:73]
	v_mfma_f32_16x16x32_bf16 v[66:69], v[180:183], v[226:229], v[66:69]
	s_setprio 0
	s_barrier
	s_add_i32 s6, s6, s31
	s_mov_b32 m0, s6
	ds_read_b128 v[184:187], v166 offset:49152
	ds_read_b128 v[188:191], v166 offset:50176
	ds_read_b128 v[200:203], v166 offset:51200
	ds_read_b128 v[204:207], v166 offset:52224
	ds_read_b128 v[214:217], v166 offset:53248
	ds_read_b128 v[218:221], v166 offset:54272
	ds_read_b128 v[222:225], v166 offset:55296
	ds_read_b128 v[226:229], v166 offset:56320
	s_add_u32 s100, s68, s72
	s_addc_u32 s101, s69, s73
	global_load_lds_dwordx4 v148, s[100:101]
	s_add_i32 m0, s6, 0x2000
	s_add_u32 s20, s68, 0x80080
	s_addc_u32 s21, s69, 0
	s_add_i32 s6, s7, s31
	global_load_lds_dwordx4 v152, s[100:101]
	s_mov_b32 m0, s6
	s_nop 0
	global_load_lds_dwordx4 v148, s[20:21]
	s_add_i32 m0, s6, 0x2000
	s_nop 0
	global_load_lds_dwordx4 v152, s[20:21]
	s_mov_b32 m0, s22
	s_nop 0
	s_add_u32 s100, vcc_lo, s72
	s_addc_u32 s101, vcc_hi, s73
	global_load_lds_dwordx4 v146, s[100:101]
	s_mov_b32 m0, s23
	s_nop 0
	global_load_lds_dwordx4 v150, s[100:101]
	s_waitcnt vmcnt(8)
	s_waitcnt lgkmcnt(0)
	s_barrier
	s_setprio 1
	s_waitcnt lgkmcnt(0)
	v_mfma_f32_16x16x32_bf16 v[62:65], v[130:133], v[184:187], v[62:65]
	v_mfma_f32_16x16x32_bf16 v[58:61], v[138:141], v[184:187], v[58:61]
	v_mfma_f32_16x16x32_bf16 v[50:53], v[130:133], v[200:203], v[50:53]
	v_mfma_f32_16x16x32_bf16 v[42:45], v[138:141], v[200:203], v[42:45]
	v_mfma_f32_16x16x32_bf16 v[34:37], v[130:133], v[214:217], v[34:37]
	v_mfma_f32_16x16x32_bf16 v[26:29], v[138:141], v[214:217], v[26:29]
	v_mfma_f32_16x16x32_bf16 v[14:17], v[130:133], v[222:225], v[14:17]
	v_mfma_f32_16x16x32_bf16 v[10:13], v[138:141], v[222:225], v[10:13]
	v_mfma_f32_16x16x32_bf16 v[62:65], v[134:137], v[188:191], v[62:65]
	v_mfma_f32_16x16x32_bf16 v[58:61], v[142:145], v[188:191], v[58:61]
	v_mfma_f32_16x16x32_bf16 v[50:53], v[134:137], v[204:207], v[50:53]
	v_mfma_f32_16x16x32_bf16 v[42:45], v[142:145], v[204:207], v[42:45]
	v_mfma_f32_16x16x32_bf16 v[34:37], v[134:137], v[218:221], v[34:37]
	v_mfma_f32_16x16x32_bf16 v[26:29], v[142:145], v[218:221], v[26:29]
	v_mfma_f32_16x16x32_bf16 v[14:17], v[134:137], v[226:229], v[14:17]
	v_mfma_f32_16x16x32_bf16 v[10:13], v[142:145], v[226:229], v[10:13]
	s_setprio 0
	s_setprio 1
	v_mfma_f32_16x16x32_bf16 v[54:57], v[168:171], v[184:187], v[54:57]
	v_mfma_f32_16x16x32_bf16 v[46:49], v[176:179], v[184:187], v[46:49]
	v_mfma_f32_16x16x32_bf16 v[38:41], v[168:171], v[200:203], v[38:41]
	v_mfma_f32_16x16x32_bf16 v[30:33], v[176:179], v[200:203], v[30:33]
	v_mfma_f32_16x16x32_bf16 v[22:25], v[168:171], v[214:217], v[22:25]
	v_mfma_f32_16x16x32_bf16 v[18:21], v[176:179], v[214:217], v[18:21]
	v_mfma_f32_16x16x32_bf16 v[6:9], v[168:171], v[222:225], v[6:9]
	v_mfma_f32_16x16x32_bf16 v[2:5], v[176:179], v[222:225], v[2:5]
	v_mfma_f32_16x16x32_bf16 v[54:57], v[172:175], v[188:191], v[54:57]
	v_mfma_f32_16x16x32_bf16 v[46:49], v[180:183], v[188:191], v[46:49]
	v_mfma_f32_16x16x32_bf16 v[38:41], v[172:175], v[204:207], v[38:41]
	v_mfma_f32_16x16x32_bf16 v[30:33], v[180:183], v[204:207], v[30:33]
	v_mfma_f32_16x16x32_bf16 v[22:25], v[172:175], v[218:221], v[22:25]
	v_mfma_f32_16x16x32_bf16 v[18:21], v[180:183], v[218:221], v[18:21]
	v_mfma_f32_16x16x32_bf16 v[6:9], v[172:175], v[226:229], v[6:9]
	v_mfma_f32_16x16x32_bf16 v[2:5], v[180:183], v[226:229], v[2:5]
	s_setprio 0
	s_barrier
	s_add_i32 s25, s25, 2
	s_add_u32 s66, s66, 0x100
	s_addc_u32 s67, s67, 0
	s_add_u32 s13, s13, 0x100
	s_addc_u32 s24, s24, 0
	s_cmp_gt_u32 s25, 29
	s_cbranch_scc0 .LBB0_167
	s_and_b64 vcc, exec, s[40:41]
	s_cbranch_vccz .LBB0_170
	s_barrier

.LBB0_356:
	s_add_u32 s66, s46, 0x100
	s_addc_u32 s67, s47, 0
	s_add_i32 s6, 0, 0x10000
	s_cmp_eq_u32 s30, 28
	s_cselect_b32 vcc_hi, s11, s67
	s_cselect_b32 vcc_lo, s29, s66
	s_cselect_b32 s69, s12, s25
	s_cselect_b32 s68, s13, s24
	s_add_i32 s7, 0, 0x14000
	v_add_u32_e32 v142, s6, v177
	v_add_u32_e32 v164, s7, v177
	ds_read_b128 v[130:133], v142
	ds_read_b128 v[134:137], v142 offset:1024
	ds_read_b128 v[138:141], v142 offset:2048
	ds_read_b128 v[142:145], v142 offset:3072
	ds_read_b128 v[146:149], v164
	ds_read_b128 v[150:153], v164 offset:1024
	ds_read_b128 v[154:157], v164 offset:2048
	ds_read_b128 v[164:167], v164 offset:3072
	s_add_i32 m0, s15, 0xc000
	ds_read_b128 v[168:171], v179
	ds_read_b128 v[172:175], v179 offset:1024
	ds_read_b128 v[180:183], v179 offset:2048
	ds_read_b128 v[184:187], v179 offset:3072
	ds_read_b128 v[188:191], v179 offset:4096
	ds_read_b128 v[200:203], v179 offset:5120
	ds_read_b128 v[204:207], v179 offset:6144
	ds_read_b128 v[214:217], v179 offset:7168
	global_load_lds_dwordx4 v160, s[46:47]
	s_add_i32 m0, s15, 0xe000
	s_nop 0
	global_load_lds_dwordx4 v162, s[46:47]
	s_waitcnt vmcnt(8)
	s_waitcnt lgkmcnt(0)
	s_barrier
	s_setprio 1
	s_waitcnt lgkmcnt(0)
	v_mfma_f32_16x16x32_bf16 v[126:129], v[130:133], v[168:171], v[126:129]
	v_mfma_f32_16x16x32_bf16 v[122:125], v[138:141], v[168:171], v[122:125]
	v_mfma_f32_16x16x32_bf16 v[110:113], v[130:133], v[180:183], v[110:113]
	v_mfma_f32_16x16x32_bf16 v[106:109], v[138:141], v[180:183], v[106:109]
	v_mfma_f32_16x16x32_bf16 v[94:97], v[130:133], v[188:191], v[94:97]
	v_mfma_f32_16x16x32_bf16 v[90:93], v[138:141], v[188:191], v[90:93]
	v_mfma_f32_16x16x32_bf16 v[78:81], v[130:133], v[204:207], v[78:81]
	v_mfma_f32_16x16x32_bf16 v[74:77], v[138:141], v[204:207], v[74:77]
	v_mfma_f32_16x16x32_bf16 v[126:129], v[134:137], v[172:175], v[126:129]
	v_mfma_f32_16x16x32_bf16 v[122:125], v[142:145], v[172:175], v[122:125]
	v_mfma_f32_16x16x32_bf16 v[110:113], v[134:137], v[184:187], v[110:113]
	v_mfma_f32_16x16x32_bf16 v[106:109], v[142:145], v[184:187], v[106:109]
	v_mfma_f32_16x16x32_bf16 v[94:97], v[134:137], v[200:203], v[94:97]
	v_mfma_f32_16x16x32_bf16 v[90:93], v[142:145], v[200:203], v[90:93]
	v_mfma_f32_16x16x32_bf16 v[78:81], v[134:137], v[214:217], v[78:81]
	v_mfma_f32_16x16x32_bf16 v[74:77], v[142:145], v[214:217], v[74:77]
	s_setprio 0
	s_setprio 1
	v_mfma_f32_16x16x32_bf16 v[118:121], v[146:149], v[168:171], v[118:121]
	v_mfma_f32_16x16x32_bf16 v[114:117], v[154:157], v[168:171], v[114:117]
	v_mfma_f32_16x16x32_bf16 v[102:105], v[146:149], v[180:183], v[102:105]
	v_mfma_f32_16x16x32_bf16 v[98:101], v[154:157], v[180:183], v[98:101]
	v_mfma_f32_16x16x32_bf16 v[86:89], v[146:149], v[188:191], v[86:89]
	v_mfma_f32_16x16x32_bf16 v[82:85], v[154:157], v[188:191], v[82:85]
	v_mfma_f32_16x16x32_bf16 v[70:73], v[146:149], v[204:207], v[70:73]
	v_mfma_f32_16x16x32_bf16 v[66:69], v[154:157], v[204:207], v[66:69]
	v_mfma_f32_16x16x32_bf16 v[118:121], v[150:153], v[172:175], v[118:121]
	v_mfma_f32_16x16x32_bf16 v[114:117], v[164:167], v[172:175], v[114:117]
	v_mfma_f32_16x16x32_bf16 v[102:105], v[150:153], v[184:187], v[102:105]
	v_mfma_f32_16x16x32_bf16 v[98:101], v[164:167], v[184:187], v[98:101]
	v_mfma_f32_16x16x32_bf16 v[86:89], v[150:153], v[200:203], v[86:89]
	v_mfma_f32_16x16x32_bf16 v[82:85], v[164:167], v[200:203], v[82:85]
	v_mfma_f32_16x16x32_bf16 v[70:73], v[150:153], v[214:217], v[70:73]
	v_mfma_f32_16x16x32_bf16 v[66:69], v[164:167], v[214:217], v[66:69]
	s_setprio 0
	s_barrier
	s_add_i32 s6, s6, s14
	s_mov_b32 m0, s6
	ds_read_b128 v[168:171], v179 offset:16384
	ds_read_b128 v[172:175], v179 offset:17408
	ds_read_b128 v[180:183], v179 offset:18432
	ds_read_b128 v[184:187], v179 offset:19456
	ds_read_b128 v[188:191], v179 offset:20480
	ds_read_b128 v[200:203], v179 offset:21504
	ds_read_b128 v[204:207], v179 offset:22528
	ds_read_b128 v[214:217], v179 offset:23552
	global_load_lds_dwordx4 v0, s[68:69]
	s_add_i32 m0, s6, 0x2000
	s_add_u32 s20, s68, 0x80000
	s_addc_u32 s21, s69, 0
	s_add_i32 s6, s7, s14
	global_load_lds_dwordx4 v158, s[68:69]
	s_mov_b32 m0, s6
	s_nop 0
	global_load_lds_dwordx4 v0, s[20:21]
	s_add_i32 m0, s6, 0x2000
	s_nop 0
	global_load_lds_dwordx4 v158, s[20:21]
	s_mov_b32 m0, s15
	s_nop 0
	global_load_lds_dwordx4 v0, vcc
	s_mov_b32 m0, s18
	s_nop 0
	global_load_lds_dwordx4 v158, vcc
	s_waitcnt vmcnt(8)
	s_waitcnt lgkmcnt(0)
	s_barrier
	s_setprio 1
	s_waitcnt lgkmcnt(0)
	v_mfma_f32_16x16x32_bf16 v[62:65], v[130:133], v[168:171], v[62:65]
	v_mfma_f32_16x16x32_bf16 v[58:61], v[138:141], v[168:171], v[58:61]
	v_mfma_f32_16x16x32_bf16 v[46:49], v[130:133], v[180:183], v[46:49]
	v_mfma_f32_16x16x32_bf16 v[42:45], v[138:141], v[180:183], v[42:45]
	v_mfma_f32_16x16x32_bf16 v[30:33], v[130:133], v[188:191], v[30:33]
	v_mfma_f32_16x16x32_bf16 v[26:29], v[138:141], v[188:191], v[26:29]
	v_mfma_f32_16x16x32_bf16 v[14:17], v[130:133], v[204:207], v[14:17]
	v_mfma_f32_16x16x32_bf16 v[10:13], v[138:141], v[204:207], v[10:13]
	v_mfma_f32_16x16x32_bf16 v[62:65], v[134:137], v[172:175], v[62:65]
	v_mfma_f32_16x16x32_bf16 v[58:61], v[142:145], v[172:175], v[58:61]
	v_mfma_f32_16x16x32_bf16 v[46:49], v[134:137], v[184:187], v[46:49]
	v_mfma_f32_16x16x32_bf16 v[42:45], v[142:145], v[184:187], v[42:45]
	v_mfma_f32_16x16x32_bf16 v[30:33], v[134:137], v[200:203], v[30:33]
	v_mfma_f32_16x16x32_bf16 v[26:29], v[142:145], v[200:203], v[26:29]
	v_mfma_f32_16x16x32_bf16 v[14:17], v[134:137], v[214:217], v[14:17]
	v_mfma_f32_16x16x32_bf16 v[10:13], v[142:145], v[214:217], v[10:13]
	s_setprio 0
	s_setprio 1
	v_mfma_f32_16x16x32_bf16 v[54:57], v[146:149], v[168:171], v[54:57]
	v_mfma_f32_16x16x32_bf16 v[50:53], v[154:157], v[168:171], v[50:53]
	v_mfma_f32_16x16x32_bf16 v[38:41], v[146:149], v[180:183], v[38:41]
	v_mfma_f32_16x16x32_bf16 v[34:37], v[154:157], v[180:183], v[34:37]
	v_mfma_f32_16x16x32_bf16 v[22:25], v[146:149], v[188:191], v[22:25]
	v_mfma_f32_16x16x32_bf16 v[18:21], v[154:157], v[188:191], v[18:21]
	v_mfma_f32_16x16x32_bf16 v[6:9], v[146:149], v[204:207], v[6:9]
	v_mfma_f32_16x16x32_bf16 v[2:5], v[154:157], v[204:207], v[2:5]
	v_mfma_f32_16x16x32_bf16 v[54:57], v[150:153], v[172:175], v[54:57]
	v_mfma_f32_16x16x32_bf16 v[50:53], v[164:167], v[172:175], v[50:53]
	v_mfma_f32_16x16x32_bf16 v[38:41], v[150:153], v[184:187], v[38:41]
	v_mfma_f32_16x16x32_bf16 v[34:37], v[164:167], v[184:187], v[34:37]
	v_mfma_f32_16x16x32_bf16 v[22:25], v[150:153], v[200:203], v[22:25]
	v_mfma_f32_16x16x32_bf16 v[18:21], v[164:167], v[200:203], v[18:21]
	v_mfma_f32_16x16x32_bf16 v[6:9], v[150:153], v[214:217], v[6:9]
	v_mfma_f32_16x16x32_bf16 v[2:5], v[164:167], v[214:217], v[2:5]
	s_setprio 0
	s_barrier
	s_add_i32 s6, 0, 0x18000
	s_add_i32 s7, 0, 0x1c000
	v_add_u32_e32 v142, s6, v177
	v_add_u32_e32 v164, s7, v177
	ds_read_b128 v[130:133], v142
	ds_read_b128 v[134:137], v142 offset:1024
	ds_read_b128 v[138:141], v142 offset:2048
	ds_read_b128 v[142:145], v142 offset:3072
	ds_read_b128 v[146:149], v164
	ds_read_b128 v[150:153], v164 offset:1024
	ds_read_b128 v[154:157], v164 offset:2048
	ds_read_b128 v[164:167], v164 offset:3072
	s_add_u32 s20, vcc_lo, 0x80000
	s_addc_u32 s21, vcc_hi, 0
	s_mov_b32 m0, s19
	ds_read_b128 v[168:171], v179 offset:32768
	ds_read_b128 v[172:175], v179 offset:33792
	ds_read_b128 v[180:183], v179 offset:34816
	ds_read_b128 v[184:187], v179 offset:35840
	ds_read_b128 v[188:191], v179 offset:36864
	ds_read_b128 v[200:203], v179 offset:37888
	ds_read_b128 v[204:207], v179 offset:38912
	ds_read_b128 v[214:217], v179 offset:39936
	global_load_lds_dwordx4 v0, s[20:21]
	s_mov_b32 m0, s27
	s_nop 0
	global_load_lds_dwordx4 v158, s[20:21]
	s_waitcnt vmcnt(8)
	s_waitcnt lgkmcnt(0)
	s_barrier
	s_setprio 1
	s_waitcnt lgkmcnt(0)
	v_mfma_f32_16x16x32_bf16 v[126:129], v[130:133], v[168:171], v[126:129]
	v_mfma_f32_16x16x32_bf16 v[122:125], v[138:141], v[168:171], v[122:125]
	v_mfma_f32_16x16x32_bf16 v[110:113], v[130:133], v[180:183], v[110:113]
	v_mfma_f32_16x16x32_bf16 v[106:109], v[138:141], v[180:183], v[106:109]
	v_mfma_f32_16x16x32_bf16 v[94:97], v[130:133], v[188:191], v[94:97]
	v_mfma_f32_16x16x32_bf16 v[90:93], v[138:141], v[188:191], v[90:93]
	v_mfma_f32_16x16x32_bf16 v[78:81], v[130:133], v[204:207], v[78:81]
	v_mfma_f32_16x16x32_bf16 v[74:77], v[138:141], v[204:207], v[74:77]
	v_mfma_f32_16x16x32_bf16 v[126:129], v[134:137], v[172:175], v[126:129]
	v_mfma_f32_16x16x32_bf16 v[122:125], v[142:145], v[172:175], v[122:125]
	v_mfma_f32_16x16x32_bf16 v[110:113], v[134:137], v[184:187], v[110:113]
	v_mfma_f32_16x16x32_bf16 v[106:109], v[142:145], v[184:187], v[106:109]
	v_mfma_f32_16x16x32_bf16 v[94:97], v[134:137], v[200:203], v[94:97]
	v_mfma_f32_16x16x32_bf16 v[90:93], v[142:145], v[200:203], v[90:93]
	v_mfma_f32_16x16x32_bf16 v[78:81], v[134:137], v[214:217], v[78:81]
	v_mfma_f32_16x16x32_bf16 v[74:77], v[142:145], v[214:217], v[74:77]
	s_setprio 0
	s_setprio 1
	v_mfma_f32_16x16x32_bf16 v[118:121], v[146:149], v[168:171], v[118:121]
	v_mfma_f32_16x16x32_bf16 v[114:117], v[154:157], v[168:171], v[114:117]
	v_mfma_f32_16x16x32_bf16 v[102:105], v[146:149], v[180:183], v[102:105]
	v_mfma_f32_16x16x32_bf16 v[98:101], v[154:157], v[180:183], v[98:101]
	v_mfma_f32_16x16x32_bf16 v[86:89], v[146:149], v[188:191], v[86:89]
	v_mfma_f32_16x16x32_bf16 v[82:85], v[154:157], v[188:191], v[82:85]
	v_mfma_f32_16x16x32_bf16 v[70:73], v[146:149], v[204:207], v[70:73]
	v_mfma_f32_16x16x32_bf16 v[66:69], v[154:157], v[204:207], v[66:69]
	v_mfma_f32_16x16x32_bf16 v[118:121], v[150:153], v[172:175], v[118:121]
	v_mfma_f32_16x16x32_bf16 v[114:117], v[164:167], v[172:175], v[114:117]
	v_mfma_f32_16x16x32_bf16 v[102:105], v[150:153], v[184:187], v[102:105]
	v_mfma_f32_16x16x32_bf16 v[98:101], v[164:167], v[184:187], v[98:101]
	v_mfma_f32_16x16x32_bf16 v[86:89], v[150:153], v[200:203], v[86:89]
	v_mfma_f32_16x16x32_bf16 v[82:85], v[164:167], v[200:203], v[82:85]
	v_mfma_f32_16x16x32_bf16 v[70:73], v[150:153], v[214:217], v[70:73]
	v_mfma_f32_16x16x32_bf16 v[66:69], v[164:167], v[214:217], v[66:69]
	s_setprio 0
	s_barrier
	s_add_i32 s6, s6, s14
	s_mov_b32 m0, s6
	ds_read_b128 v[168:171], v179 offset:49152
	ds_read_b128 v[172:175], v179 offset:50176
	ds_read_b128 v[180:183], v179 offset:51200
	ds_read_b128 v[184:187], v179 offset:52224
	ds_read_b128 v[188:191], v179 offset:53248
	ds_read_b128 v[200:203], v179 offset:54272
	ds_read_b128 v[204:207], v179 offset:55296
	ds_read_b128 v[214:217], v179 offset:56320
	s_add_u32 s100, s68, s72
	s_addc_u32 s101, s69, s73
	global_load_lds_dwordx4 v0, s[100:101]
	s_add_i32 m0, s6, 0x2000
	s_add_u32 s20, s68, 0x80080
	s_addc_u32 s21, s69, 0
	s_add_i32 s6, s7, s14
	global_load_lds_dwordx4 v158, s[100:101]
	s_mov_b32 m0, s6
	s_nop 0
	global_load_lds_dwordx4 v0, s[20:21]
	s_add_i32 m0, s6, 0x2000
	s_nop 0
	global_load_lds_dwordx4 v158, s[20:21]
	s_mov_b32 m0, s23
	s_nop 0
	s_add_u32 s100, vcc_lo, s72
	s_addc_u32 s101, vcc_hi, s73
	global_load_lds_dwordx4 v0, s[100:101]
	s_mov_b32 m0, s28
	s_nop 0
	global_load_lds_dwordx4 v158, s[100:101]
	s_waitcnt vmcnt(8)
	s_waitcnt lgkmcnt(0)
	s_barrier
	s_setprio 1
	s_waitcnt lgkmcnt(0)
	v_mfma_f32_16x16x32_bf16 v[62:65], v[130:133], v[168:171], v[62:65]
	v_mfma_f32_16x16x32_bf16 v[58:61], v[138:141], v[168:171], v[58:61]
	v_mfma_f32_16x16x32_bf16 v[46:49], v[130:133], v[180:183], v[46:49]
	v_mfma_f32_16x16x32_bf16 v[42:45], v[138:141], v[180:183], v[42:45]
	v_mfma_f32_16x16x32_bf16 v[30:33], v[130:133], v[188:191], v[30:33]
	v_mfma_f32_16x16x32_bf16 v[26:29], v[138:141], v[188:191], v[26:29]
	v_mfma_f32_16x16x32_bf16 v[14:17], v[130:133], v[204:207], v[14:17]
	v_mfma_f32_16x16x32_bf16 v[10:13], v[138:141], v[204:207], v[10:13]
	v_mfma_f32_16x16x32_bf16 v[62:65], v[134:137], v[172:175], v[62:65]
	v_mfma_f32_16x16x32_bf16 v[58:61], v[142:145], v[172:175], v[58:61]
	v_mfma_f32_16x16x32_bf16 v[46:49], v[134:137], v[184:187], v[46:49]
	v_mfma_f32_16x16x32_bf16 v[42:45], v[142:145], v[184:187], v[42:45]
	v_mfma_f32_16x16x32_bf16 v[30:33], v[134:137], v[200:203], v[30:33]
	v_mfma_f32_16x16x32_bf16 v[26:29], v[142:145], v[200:203], v[26:29]
	v_mfma_f32_16x16x32_bf16 v[14:17], v[134:137], v[214:217], v[14:17]
	v_mfma_f32_16x16x32_bf16 v[10:13], v[142:145], v[214:217], v[10:13]
	s_setprio 0
	s_setprio 1
	v_mfma_f32_16x16x32_bf16 v[54:57], v[146:149], v[168:171], v[54:57]
	v_mfma_f32_16x16x32_bf16 v[50:53], v[154:157], v[168:171], v[50:53]
	v_mfma_f32_16x16x32_bf16 v[38:41], v[146:149], v[180:183], v[38:41]
	v_mfma_f32_16x16x32_bf16 v[34:37], v[154:157], v[180:183], v[34:37]
	v_mfma_f32_16x16x32_bf16 v[22:25], v[146:149], v[188:191], v[22:25]
	v_mfma_f32_16x16x32_bf16 v[18:21], v[154:157], v[188:191], v[18:21]
	v_mfma_f32_16x16x32_bf16 v[6:9], v[146:149], v[204:207], v[6:9]
	v_mfma_f32_16x16x32_bf16 v[2:5], v[154:157], v[204:207], v[2:5]
	v_mfma_f32_16x16x32_bf16 v[54:57], v[150:153], v[172:175], v[54:57]
	v_mfma_f32_16x16x32_bf16 v[50:53], v[164:167], v[172:175], v[50:53]
	v_mfma_f32_16x16x32_bf16 v[38:41], v[150:153], v[184:187], v[38:41]
	v_mfma_f32_16x16x32_bf16 v[34:37], v[164:167], v[184:187], v[34:37]
	v_mfma_f32_16x16x32_bf16 v[22:25], v[150:153], v[200:203], v[22:25]
	v_mfma_f32_16x16x32_bf16 v[18:21], v[164:167], v[200:203], v[18:21]
	v_mfma_f32_16x16x32_bf16 v[6:9], v[150:153], v[214:217], v[6:9]
	v_mfma_f32_16x16x32_bf16 v[2:5], v[164:167], v[214:217], v[2:5]
	s_setprio 0
	s_barrier
	s_add_i32 s30, s30, 2
	s_add_u32 s24, s24, 0x100
	s_addc_u32 s25, s25, 0
	s_cmp_gt_u32 s30, 29
	s_mov_b64 s[46:47], s[66:67]
	s_cbranch_scc0 .LBB0_356
	s_and_b64 vcc, exec, s[56:57]
	s_cbranch_vccz .LBB0_359
	s_barrier

.LBB0_510:
	s_add_u32 s6, s56, 0xfff80080
	s_addc_u32 s7, s57, -1
	s_add_i32 s20, 0, 0x10000
	s_cmp_eq_u32 s23, 28
	s_cselect_b32 s61, s11, s7
	s_cselect_b32 s60, s18, s6
	v_add_u32_e32 v144, s20, v147
	s_cselect_b32 s59, s19, s22
	s_cselect_b32 s58, s12, s13
	s_add_i32 s6, 0, 0x14000
	ds_read_b128 v[140:143], v144
	ds_read_b128 v[152:155], v144 offset:1024
	ds_read_b128 v[156:159], v144 offset:2048
	ds_read_b128 v[160:163], v144 offset:3072
	v_add_u32_e32 v144, s6, v147
	ds_read_b128 v[164:167], v144
	ds_read_b128 v[168:171], v144 offset:1024
	ds_read_b128 v[172:175], v144 offset:2048
	ds_read_b128 v[176:179], v144 offset:3072
	s_add_i32 m0, s28, 0xc000
	ds_read_b128 v[180:183], v150
	ds_read_b128 v[184:187], v150 offset:1024
	ds_read_b128 v[188:191], v150 offset:2048
	ds_read_b128 v[200:203], v150 offset:3072
	ds_read_b128 v[204:207], v150 offset:4096
	ds_read_b128 v[214:217], v150 offset:5120
	ds_read_b128 v[218:221], v150 offset:6144
	ds_read_b128 v[222:225], v150 offset:7168
	global_load_lds_dwordx4 v136, s[56:57]
	s_add_i32 m0, s28, 0xe000
	s_nop 0
	global_load_lds_dwordx4 v138, s[56:57]
	s_waitcnt vmcnt(8)
	s_waitcnt lgkmcnt(0)
	s_barrier
	s_setprio 1
	s_waitcnt lgkmcnt(0)
	v_mfma_f32_16x16x32_bf16 v[126:129], v[140:143], v[180:183], v[126:129]
	v_mfma_f32_16x16x32_bf16 v[122:125], v[156:159], v[180:183], v[122:125]
	v_mfma_f32_16x16x32_bf16 v[110:113], v[140:143], v[188:191], v[110:113]
	v_mfma_f32_16x16x32_bf16 v[106:109], v[156:159], v[188:191], v[106:109]
	v_mfma_f32_16x16x32_bf16 v[94:97], v[140:143], v[204:207], v[94:97]
	v_mfma_f32_16x16x32_bf16 v[90:93], v[156:159], v[204:207], v[90:93]
	v_mfma_f32_16x16x32_bf16 v[78:81], v[140:143], v[218:221], v[78:81]
	v_mfma_f32_16x16x32_bf16 v[74:77], v[156:159], v[218:221], v[74:77]
	v_mfma_f32_16x16x32_bf16 v[126:129], v[152:155], v[184:187], v[126:129]
	v_mfma_f32_16x16x32_bf16 v[122:125], v[160:163], v[184:187], v[122:125]
	v_mfma_f32_16x16x32_bf16 v[110:113], v[152:155], v[200:203], v[110:113]
	v_mfma_f32_16x16x32_bf16 v[106:109], v[160:163], v[200:203], v[106:109]
	v_mfma_f32_16x16x32_bf16 v[94:97], v[152:155], v[214:217], v[94:97]
	v_mfma_f32_16x16x32_bf16 v[90:93], v[160:163], v[214:217], v[90:93]
	v_mfma_f32_16x16x32_bf16 v[78:81], v[152:155], v[222:225], v[78:81]
	v_mfma_f32_16x16x32_bf16 v[74:77], v[160:163], v[222:225], v[74:77]
	s_setprio 0
	s_setprio 1
	v_mfma_f32_16x16x32_bf16 v[118:121], v[164:167], v[180:183], v[118:121]
	v_mfma_f32_16x16x32_bf16 v[114:117], v[172:175], v[180:183], v[114:117]
	v_mfma_f32_16x16x32_bf16 v[102:105], v[164:167], v[188:191], v[102:105]
	v_mfma_f32_16x16x32_bf16 v[98:101], v[172:175], v[188:191], v[98:101]
	v_mfma_f32_16x16x32_bf16 v[86:89], v[164:167], v[204:207], v[86:89]
	v_mfma_f32_16x16x32_bf16 v[82:85], v[172:175], v[204:207], v[82:85]
	v_mfma_f32_16x16x32_bf16 v[70:73], v[164:167], v[218:221], v[70:73]
	v_mfma_f32_16x16x32_bf16 v[66:69], v[172:175], v[218:221], v[66:69]
	v_mfma_f32_16x16x32_bf16 v[118:121], v[168:171], v[184:187], v[118:121]
	v_mfma_f32_16x16x32_bf16 v[114:117], v[176:179], v[184:187], v[114:117]
	v_mfma_f32_16x16x32_bf16 v[102:105], v[168:171], v[200:203], v[102:105]
	v_mfma_f32_16x16x32_bf16 v[98:101], v[176:179], v[200:203], v[98:101]
	v_mfma_f32_16x16x32_bf16 v[86:89], v[168:171], v[214:217], v[86:89]
	v_mfma_f32_16x16x32_bf16 v[82:85], v[176:179], v[214:217], v[82:85]
	v_mfma_f32_16x16x32_bf16 v[70:73], v[168:171], v[222:225], v[70:73]
	v_mfma_f32_16x16x32_bf16 v[66:69], v[176:179], v[222:225], v[66:69]
	s_setprio 0
	s_barrier
	s_add_i32 s7, s20, s14
	s_mov_b32 m0, s7
	ds_read_b128 v[180:183], v150 offset:16384
	ds_read_b128 v[184:187], v150 offset:17408
	ds_read_b128 v[188:191], v150 offset:18432
	ds_read_b128 v[200:203], v150 offset:19456
	ds_read_b128 v[204:207], v150 offset:20480
	ds_read_b128 v[214:217], v150 offset:21504
	ds_read_b128 v[218:221], v150 offset:22528
	ds_read_b128 v[222:225], v150 offset:23552
	global_load_lds_dwordx4 v0, s[58:59]
	s_add_i32 m0, s7, 0x2000
	s_add_u32 s20, s58, 0x80000
	s_addc_u32 s21, s59, 0
	s_add_i32 s6, s6, s14
	global_load_lds_dwordx4 v130, s[58:59]
	s_mov_b32 m0, s6
	s_nop 0
	global_load_lds_dwordx4 v0, s[20:21]
	s_add_i32 m0, s6, 0x2000
	s_nop 0
	global_load_lds_dwordx4 v130, s[20:21]
	s_mov_b32 m0, s28
	s_nop 0
	global_load_lds_dwordx4 v134, s[60:61]
	s_mov_b32 m0, s29
	s_nop 0
	global_load_lds_dwordx4 v132, s[60:61]
	s_waitcnt vmcnt(8)
	s_waitcnt lgkmcnt(0)
	s_barrier
	s_setprio 1
	s_waitcnt lgkmcnt(0)
	v_mfma_f32_16x16x32_bf16 v[62:65], v[140:143], v[180:183], v[62:65]
	v_mfma_f32_16x16x32_bf16 v[58:61], v[156:159], v[180:183], v[58:61]
	v_mfma_f32_16x16x32_bf16 v[46:49], v[140:143], v[188:191], v[46:49]
	v_mfma_f32_16x16x32_bf16 v[42:45], v[156:159], v[188:191], v[42:45]
	v_mfma_f32_16x16x32_bf16 v[30:33], v[140:143], v[204:207], v[30:33]
	v_mfma_f32_16x16x32_bf16 v[26:29], v[156:159], v[204:207], v[26:29]
	v_mfma_f32_16x16x32_bf16 v[14:17], v[140:143], v[218:221], v[14:17]
	v_mfma_f32_16x16x32_bf16 v[10:13], v[156:159], v[218:221], v[10:13]
	v_mfma_f32_16x16x32_bf16 v[62:65], v[152:155], v[184:187], v[62:65]
	v_mfma_f32_16x16x32_bf16 v[58:61], v[160:163], v[184:187], v[58:61]
	v_mfma_f32_16x16x32_bf16 v[46:49], v[152:155], v[200:203], v[46:49]
	v_mfma_f32_16x16x32_bf16 v[42:45], v[160:163], v[200:203], v[42:45]
	v_mfma_f32_16x16x32_bf16 v[30:33], v[152:155], v[214:217], v[30:33]
	v_mfma_f32_16x16x32_bf16 v[26:29], v[160:163], v[214:217], v[26:29]
	v_mfma_f32_16x16x32_bf16 v[14:17], v[152:155], v[222:225], v[14:17]
	v_mfma_f32_16x16x32_bf16 v[10:13], v[160:163], v[222:225], v[10:13]
	s_setprio 0
	s_setprio 1
	v_mfma_f32_16x16x32_bf16 v[54:57], v[164:167], v[180:183], v[54:57]
	v_mfma_f32_16x16x32_bf16 v[50:53], v[172:175], v[180:183], v[50:53]
	v_mfma_f32_16x16x32_bf16 v[38:41], v[164:167], v[188:191], v[38:41]
	v_mfma_f32_16x16x32_bf16 v[34:37], v[172:175], v[188:191], v[34:37]
	v_mfma_f32_16x16x32_bf16 v[22:25], v[164:167], v[204:207], v[22:25]
	v_mfma_f32_16x16x32_bf16 v[18:21], v[172:175], v[204:207], v[18:21]
	v_mfma_f32_16x16x32_bf16 v[6:9], v[164:167], v[218:221], v[6:9]
	v_mfma_f32_16x16x32_bf16 v[2:5], v[172:175], v[218:221], v[2:5]
	v_mfma_f32_16x16x32_bf16 v[54:57], v[168:171], v[184:187], v[54:57]
	v_mfma_f32_16x16x32_bf16 v[50:53], v[176:179], v[184:187], v[50:53]
	v_mfma_f32_16x16x32_bf16 v[38:41], v[168:171], v[200:203], v[38:41]
	v_mfma_f32_16x16x32_bf16 v[34:37], v[176:179], v[200:203], v[34:37]
	v_mfma_f32_16x16x32_bf16 v[22:25], v[168:171], v[214:217], v[22:25]
	v_mfma_f32_16x16x32_bf16 v[18:21], v[176:179], v[214:217], v[18:21]
	v_mfma_f32_16x16x32_bf16 v[6:9], v[168:171], v[222:225], v[6:9]
	v_mfma_f32_16x16x32_bf16 v[2:5], v[176:179], v[222:225], v[2:5]
	s_setprio 0
	s_barrier
	s_add_i32 s6, 0, 0x18000
	v_add_u32_e32 v151, s6, v147
	s_add_i32 s7, 0, 0x1c000
	ds_read_b128 v[140:143], v151
	ds_read_b128 v[152:155], v151 offset:1024
	ds_read_b128 v[156:159], v151 offset:2048
	ds_read_b128 v[160:163], v151 offset:3072
	v_add_u32_e32 v151, s7, v147
	ds_read_b128 v[164:167], v151
	ds_read_b128 v[168:171], v151 offset:1024
	ds_read_b128 v[172:175], v151 offset:2048
	ds_read_b128 v[176:179], v151 offset:3072
	s_add_u32 s20, s60, 0x80000
	s_addc_u32 s21, s61, 0
	s_mov_b32 m0, s30
	ds_read_b128 v[180:183], v150 offset:32768
	ds_read_b128 v[184:187], v150 offset:33792
	ds_read_b128 v[188:191], v150 offset:34816
	ds_read_b128 v[200:203], v150 offset:35840
	ds_read_b128 v[204:207], v150 offset:36864
	ds_read_b128 v[214:217], v150 offset:37888
	ds_read_b128 v[218:221], v150 offset:38912
	ds_read_b128 v[222:225], v150 offset:39936
	global_load_lds_dwordx4 v134, s[20:21]
	s_mov_b32 m0, s31
	s_nop 0
	global_load_lds_dwordx4 v132, s[20:21]
	s_waitcnt vmcnt(8)
	s_waitcnt lgkmcnt(0)
	s_barrier
	s_setprio 1
	s_waitcnt lgkmcnt(0)
	v_mfma_f32_16x16x32_bf16 v[126:129], v[140:143], v[180:183], v[126:129]
	v_mfma_f32_16x16x32_bf16 v[122:125], v[156:159], v[180:183], v[122:125]
	v_mfma_f32_16x16x32_bf16 v[110:113], v[140:143], v[188:191], v[110:113]
	v_mfma_f32_16x16x32_bf16 v[106:109], v[156:159], v[188:191], v[106:109]
	v_mfma_f32_16x16x32_bf16 v[94:97], v[140:143], v[204:207], v[94:97]
	v_mfma_f32_16x16x32_bf16 v[90:93], v[156:159], v[204:207], v[90:93]
	v_mfma_f32_16x16x32_bf16 v[78:81], v[140:143], v[218:221], v[78:81]
	v_mfma_f32_16x16x32_bf16 v[74:77], v[156:159], v[218:221], v[74:77]
	v_mfma_f32_16x16x32_bf16 v[126:129], v[152:155], v[184:187], v[126:129]
	v_mfma_f32_16x16x32_bf16 v[122:125], v[160:163], v[184:187], v[122:125]
	v_mfma_f32_16x16x32_bf16 v[110:113], v[152:155], v[200:203], v[110:113]
	v_mfma_f32_16x16x32_bf16 v[106:109], v[160:163], v[200:203], v[106:109]
	v_mfma_f32_16x16x32_bf16 v[94:97], v[152:155], v[214:217], v[94:97]
	v_mfma_f32_16x16x32_bf16 v[90:93], v[160:163], v[214:217], v[90:93]
	v_mfma_f32_16x16x32_bf16 v[78:81], v[152:155], v[222:225], v[78:81]
	v_mfma_f32_16x16x32_bf16 v[74:77], v[160:163], v[222:225], v[74:77]
	s_setprio 0
	s_setprio 1
	v_mfma_f32_16x16x32_bf16 v[118:121], v[164:167], v[180:183], v[118:121]
	v_mfma_f32_16x16x32_bf16 v[114:117], v[172:175], v[180:183], v[114:117]
	v_mfma_f32_16x16x32_bf16 v[102:105], v[164:167], v[188:191], v[102:105]
	v_mfma_f32_16x16x32_bf16 v[98:101], v[172:175], v[188:191], v[98:101]
	v_mfma_f32_16x16x32_bf16 v[86:89], v[164:167], v[204:207], v[86:89]
	v_mfma_f32_16x16x32_bf16 v[82:85], v[172:175], v[204:207], v[82:85]
	v_mfma_f32_16x16x32_bf16 v[70:73], v[164:167], v[218:221], v[70:73]
	v_mfma_f32_16x16x32_bf16 v[66:69], v[172:175], v[218:221], v[66:69]
	v_mfma_f32_16x16x32_bf16 v[118:121], v[168:171], v[184:187], v[118:121]
	v_mfma_f32_16x16x32_bf16 v[114:117], v[176:179], v[184:187], v[114:117]
	v_mfma_f32_16x16x32_bf16 v[102:105], v[168:171], v[200:203], v[102:105]
	v_mfma_f32_16x16x32_bf16 v[98:101], v[176:179], v[200:203], v[98:101]
	v_mfma_f32_16x16x32_bf16 v[86:89], v[168:171], v[214:217], v[86:89]
	v_mfma_f32_16x16x32_bf16 v[82:85], v[176:179], v[214:217], v[82:85]
	v_mfma_f32_16x16x32_bf16 v[70:73], v[168:171], v[222:225], v[70:73]
	v_mfma_f32_16x16x32_bf16 v[66:69], v[176:179], v[222:225], v[66:69]
	s_setprio 0
	s_barrier
	s_add_i32 s6, s6, s14
	s_mov_b32 m0, s6
	ds_read_b128 v[180:183], v150 offset:49152
	ds_read_b128 v[184:187], v150 offset:50176
	ds_read_b128 v[188:191], v150 offset:51200
	ds_read_b128 v[200:203], v150 offset:52224
	ds_read_b128 v[204:207], v150 offset:53248
	ds_read_b128 v[214:217], v150 offset:54272
	ds_read_b128 v[218:221], v150 offset:55296
	ds_read_b128 v[222:225], v150 offset:56320
	s_add_u32 s100, s58, s72
	s_addc_u32 s101, s59, s73
	global_load_lds_dwordx4 v0, s[100:101]
	s_add_i32 m0, s6, 0x2000
	s_add_u32 s20, s58, 0x80080
	s_addc_u32 s21, s59, 0
	s_add_i32 s6, s7, s14
	global_load_lds_dwordx4 v130, s[100:101]
	s_mov_b32 m0, s6
	s_nop 0
	global_load_lds_dwordx4 v0, s[20:21]
	s_add_i32 m0, s6, 0x2000
	s_nop 0
	global_load_lds_dwordx4 v130, s[20:21]
	s_mov_b32 m0, s62
	s_nop 0
	s_add_u32 s100, s60, s72
	s_addc_u32 s101, s61, s73
	global_load_lds_dwordx4 v134, s[100:101]
	s_mov_b32 m0, s63
	s_nop 0
	global_load_lds_dwordx4 v132, s[100:101]
	s_waitcnt vmcnt(8)
	s_waitcnt lgkmcnt(0)
	s_barrier
	s_setprio 1
	s_waitcnt lgkmcnt(0)
	v_mfma_f32_16x16x32_bf16 v[62:65], v[140:143], v[180:183], v[62:65]
	v_mfma_f32_16x16x32_bf16 v[58:61], v[156:159], v[180:183], v[58:61]
	v_mfma_f32_16x16x32_bf16 v[46:49], v[140:143], v[188:191], v[46:49]
	v_mfma_f32_16x16x32_bf16 v[42:45], v[156:159], v[188:191], v[42:45]
	v_mfma_f32_16x16x32_bf16 v[30:33], v[140:143], v[204:207], v[30:33]
	v_mfma_f32_16x16x32_bf16 v[26:29], v[156:159], v[204:207], v[26:29]
	v_mfma_f32_16x16x32_bf16 v[14:17], v[140:143], v[218:221], v[14:17]
	v_mfma_f32_16x16x32_bf16 v[10:13], v[156:159], v[218:221], v[10:13]
	v_mfma_f32_16x16x32_bf16 v[62:65], v[152:155], v[184:187], v[62:65]
	v_mfma_f32_16x16x32_bf16 v[58:61], v[160:163], v[184:187], v[58:61]
	v_mfma_f32_16x16x32_bf16 v[46:49], v[152:155], v[200:203], v[46:49]
	v_mfma_f32_16x16x32_bf16 v[42:45], v[160:163], v[200:203], v[42:45]
	v_mfma_f32_16x16x32_bf16 v[30:33], v[152:155], v[214:217], v[30:33]
	v_mfma_f32_16x16x32_bf16 v[26:29], v[160:163], v[214:217], v[26:29]
	v_mfma_f32_16x16x32_bf16 v[14:17], v[152:155], v[222:225], v[14:17]
	v_mfma_f32_16x16x32_bf16 v[10:13], v[160:163], v[222:225], v[10:13]
	s_setprio 0
	s_setprio 1
	v_mfma_f32_16x16x32_bf16 v[54:57], v[164:167], v[180:183], v[54:57]
	v_mfma_f32_16x16x32_bf16 v[50:53], v[172:175], v[180:183], v[50:53]
	v_mfma_f32_16x16x32_bf16 v[38:41], v[164:167], v[188:191], v[38:41]
	v_mfma_f32_16x16x32_bf16 v[34:37], v[172:175], v[188:191], v[34:37]
	v_mfma_f32_16x16x32_bf16 v[22:25], v[164:167], v[204:207], v[22:25]
	v_mfma_f32_16x16x32_bf16 v[18:21], v[172:175], v[204:207], v[18:21]
	v_mfma_f32_16x16x32_bf16 v[6:9], v[164:167], v[218:221], v[6:9]
	v_mfma_f32_16x16x32_bf16 v[2:5], v[172:175], v[218:221], v[2:5]
	v_mfma_f32_16x16x32_bf16 v[54:57], v[168:171], v[184:187], v[54:57]
	v_mfma_f32_16x16x32_bf16 v[50:53], v[176:179], v[184:187], v[50:53]
	v_mfma_f32_16x16x32_bf16 v[38:41], v[168:171], v[200:203], v[38:41]
	v_mfma_f32_16x16x32_bf16 v[34:37], v[176:179], v[200:203], v[34:37]
	v_mfma_f32_16x16x32_bf16 v[22:25], v[168:171], v[214:217], v[22:25]
	v_mfma_f32_16x16x32_bf16 v[18:21], v[176:179], v[214:217], v[18:21]
	v_mfma_f32_16x16x32_bf16 v[6:9], v[168:171], v[222:225], v[6:9]
	v_mfma_f32_16x16x32_bf16 v[2:5], v[176:179], v[222:225], v[2:5]
	s_setprio 0
	s_barrier
	s_add_i32 s23, s23, 2
	s_add_u32 s56, s56, 0x100
	s_addc_u32 s57, s57, 0
	s_add_u32 s13, s13, 0x100
	s_addc_u32 s22, s22, 0
	s_cmp_gt_u32 s23, 29
	s_cbranch_scc0 .LBB0_510
	s_and_b64 vcc, exec, s[44:45]
	s_cbranch_vccz .LBB0_513
	s_barrier

.LBB0_586:
	s_add_u32 s44, s56, 0x100
	s_addc_u32 s45, s57, 0
	s_add_i32 s6, 0, 0x10000
	s_cmpk_eq_i32 s13, 0x54
	s_cselect_b32 s61, s53, s45
	s_cselect_b32 s60, s52, s44
	s_cselect_b32 s59, s55, s12
	s_cselect_b32 s58, s54, s11
	s_add_i32 s7, 0, 0x14000
	v_add_u32_e32 v142, s6, v179
	v_add_u32_e32 v164, s7, v179
	ds_read_b128 v[130:133], v142
	ds_read_b128 v[134:137], v142 offset:1024
	ds_read_b128 v[138:141], v142 offset:2048
	ds_read_b128 v[142:145], v142 offset:3072
	ds_read_b128 v[146:149], v164
	ds_read_b128 v[150:153], v164 offset:1024
	ds_read_b128 v[154:157], v164 offset:2048
	ds_read_b128 v[164:167], v164 offset:3072
	s_add_i32 m0, s18, 0xc000
	ds_read_b128 v[168:171], v181
	ds_read_b128 v[172:175], v181 offset:1024
	ds_read_b128 v[182:185], v181 offset:2048
	ds_read_b128 v[186:189], v181 offset:3072
	ds_read_b128 v[190:193], v181 offset:4096
	ds_read_b128 v[200:203], v181 offset:5120
	ds_read_b128 v[204:207], v181 offset:6144
	ds_read_b128 v[214:217], v181 offset:7168
	global_load_lds_dwordx4 v160, s[56:57]
	s_add_i32 m0, s18, 0xe000
	s_nop 0
	global_load_lds_dwordx4 v162, s[56:57]
	s_waitcnt vmcnt(8)
	s_waitcnt lgkmcnt(0)
	s_barrier
	s_setprio 1
	s_waitcnt lgkmcnt(0)
	v_mfma_f32_16x16x32_bf16 v[126:129], v[130:133], v[168:171], v[126:129]
	v_mfma_f32_16x16x32_bf16 v[122:125], v[138:141], v[168:171], v[122:125]
	v_mfma_f32_16x16x32_bf16 v[110:113], v[130:133], v[182:185], v[110:113]
	v_mfma_f32_16x16x32_bf16 v[106:109], v[138:141], v[182:185], v[106:109]
	v_mfma_f32_16x16x32_bf16 v[94:97], v[130:133], v[190:193], v[94:97]
	v_mfma_f32_16x16x32_bf16 v[90:93], v[138:141], v[190:193], v[90:93]
	v_mfma_f32_16x16x32_bf16 v[78:81], v[130:133], v[204:207], v[78:81]
	v_mfma_f32_16x16x32_bf16 v[74:77], v[138:141], v[204:207], v[74:77]
	v_mfma_f32_16x16x32_bf16 v[126:129], v[134:137], v[172:175], v[126:129]
	v_mfma_f32_16x16x32_bf16 v[122:125], v[142:145], v[172:175], v[122:125]
	v_mfma_f32_16x16x32_bf16 v[110:113], v[134:137], v[186:189], v[110:113]
	v_mfma_f32_16x16x32_bf16 v[106:109], v[142:145], v[186:189], v[106:109]
	v_mfma_f32_16x16x32_bf16 v[94:97], v[134:137], v[200:203], v[94:97]
	v_mfma_f32_16x16x32_bf16 v[90:93], v[142:145], v[200:203], v[90:93]
	v_mfma_f32_16x16x32_bf16 v[78:81], v[134:137], v[214:217], v[78:81]
	v_mfma_f32_16x16x32_bf16 v[74:77], v[142:145], v[214:217], v[74:77]
	s_setprio 0
	s_setprio 1
	v_mfma_f32_16x16x32_bf16 v[118:121], v[146:149], v[168:171], v[118:121]
	v_mfma_f32_16x16x32_bf16 v[114:117], v[154:157], v[168:171], v[114:117]
	v_mfma_f32_16x16x32_bf16 v[102:105], v[146:149], v[182:185], v[102:105]
	v_mfma_f32_16x16x32_bf16 v[98:101], v[154:157], v[182:185], v[98:101]
	v_mfma_f32_16x16x32_bf16 v[86:89], v[146:149], v[190:193], v[86:89]
	v_mfma_f32_16x16x32_bf16 v[82:85], v[154:157], v[190:193], v[82:85]
	v_mfma_f32_16x16x32_bf16 v[70:73], v[146:149], v[204:207], v[70:73]
	v_mfma_f32_16x16x32_bf16 v[66:69], v[154:157], v[204:207], v[66:69]
	v_mfma_f32_16x16x32_bf16 v[118:121], v[150:153], v[172:175], v[118:121]
	v_mfma_f32_16x16x32_bf16 v[114:117], v[164:167], v[172:175], v[114:117]
	v_mfma_f32_16x16x32_bf16 v[102:105], v[150:153], v[186:189], v[102:105]
	v_mfma_f32_16x16x32_bf16 v[98:101], v[164:167], v[186:189], v[98:101]
	v_mfma_f32_16x16x32_bf16 v[86:89], v[150:153], v[200:203], v[86:89]
	v_mfma_f32_16x16x32_bf16 v[82:85], v[164:167], v[200:203], v[82:85]
	v_mfma_f32_16x16x32_bf16 v[70:73], v[150:153], v[214:217], v[70:73]
	v_mfma_f32_16x16x32_bf16 v[66:69], v[164:167], v[214:217], v[66:69]
	s_setprio 0
	s_barrier
	s_add_i32 s6, s6, s29
	s_mov_b32 m0, s6
	ds_read_b128 v[168:171], v181 offset:16384
	ds_read_b128 v[172:175], v181 offset:17408
	ds_read_b128 v[182:185], v181 offset:18432
	ds_read_b128 v[186:189], v181 offset:19456
	ds_read_b128 v[190:193], v181 offset:20480
	ds_read_b128 v[200:203], v181 offset:21504
	ds_read_b128 v[204:207], v181 offset:22528
	ds_read_b128 v[214:217], v181 offset:23552
	global_load_lds_dwordx4 v0, s[58:59]
	s_add_i32 m0, s6, 0x2000
	s_add_u32 s20, s58, 0x160000
	s_addc_u32 s21, s59, 0
	s_add_i32 s6, s7, s29
	global_load_lds_dwordx4 v158, s[58:59]
	s_mov_b32 m0, s6
	s_nop 0
	global_load_lds_dwordx4 v0, s[20:21]
	s_add_i32 m0, s6, 0x2000
	s_nop 0
	global_load_lds_dwordx4 v158, s[20:21]
	s_mov_b32 m0, s18
	s_nop 0
	global_load_lds_dwordx4 v0, s[60:61]
	s_mov_b32 m0, s19
	s_nop 0
	global_load_lds_dwordx4 v158, s[60:61]
	s_waitcnt vmcnt(8)
	s_waitcnt lgkmcnt(0)
	s_barrier
	s_setprio 1
	s_waitcnt lgkmcnt(0)
	v_mfma_f32_16x16x32_bf16 v[62:65], v[130:133], v[168:171], v[62:65]
	v_mfma_f32_16x16x32_bf16 v[58:61], v[138:141], v[168:171], v[58:61]
	v_mfma_f32_16x16x32_bf16 v[46:49], v[130:133], v[182:185], v[46:49]
	v_mfma_f32_16x16x32_bf16 v[42:45], v[138:141], v[182:185], v[42:45]
	v_mfma_f32_16x16x32_bf16 v[30:33], v[130:133], v[190:193], v[30:33]
	v_mfma_f32_16x16x32_bf16 v[26:29], v[138:141], v[190:193], v[26:29]
	v_mfma_f32_16x16x32_bf16 v[14:17], v[130:133], v[204:207], v[14:17]
	v_mfma_f32_16x16x32_bf16 v[10:13], v[138:141], v[204:207], v[10:13]
	v_mfma_f32_16x16x32_bf16 v[62:65], v[134:137], v[172:175], v[62:65]
	v_mfma_f32_16x16x32_bf16 v[58:61], v[142:145], v[172:175], v[58:61]
	v_mfma_f32_16x16x32_bf16 v[46:49], v[134:137], v[186:189], v[46:49]
	v_mfma_f32_16x16x32_bf16 v[42:45], v[142:145], v[186:189], v[42:45]
	v_mfma_f32_16x16x32_bf16 v[30:33], v[134:137], v[200:203], v[30:33]
	v_mfma_f32_16x16x32_bf16 v[26:29], v[142:145], v[200:203], v[26:29]
	v_mfma_f32_16x16x32_bf16 v[14:17], v[134:137], v[214:217], v[14:17]
	v_mfma_f32_16x16x32_bf16 v[10:13], v[142:145], v[214:217], v[10:13]
	s_setprio 0
	s_setprio 1
	v_mfma_f32_16x16x32_bf16 v[54:57], v[146:149], v[168:171], v[54:57]
	v_mfma_f32_16x16x32_bf16 v[50:53], v[154:157], v[168:171], v[50:53]
	v_mfma_f32_16x16x32_bf16 v[38:41], v[146:149], v[182:185], v[38:41]
	v_mfma_f32_16x16x32_bf16 v[34:37], v[154:157], v[182:185], v[34:37]
	v_mfma_f32_16x16x32_bf16 v[22:25], v[146:149], v[190:193], v[22:25]
	v_mfma_f32_16x16x32_bf16 v[18:21], v[154:157], v[190:193], v[18:21]
	v_mfma_f32_16x16x32_bf16 v[6:9], v[146:149], v[204:207], v[6:9]
	v_mfma_f32_16x16x32_bf16 v[2:5], v[154:157], v[204:207], v[2:5]
	v_mfma_f32_16x16x32_bf16 v[54:57], v[150:153], v[172:175], v[54:57]
	v_mfma_f32_16x16x32_bf16 v[50:53], v[164:167], v[172:175], v[50:53]
	v_mfma_f32_16x16x32_bf16 v[38:41], v[150:153], v[186:189], v[38:41]
	v_mfma_f32_16x16x32_bf16 v[34:37], v[164:167], v[186:189], v[34:37]
	v_mfma_f32_16x16x32_bf16 v[22:25], v[150:153], v[200:203], v[22:25]
	v_mfma_f32_16x16x32_bf16 v[18:21], v[164:167], v[200:203], v[18:21]
	v_mfma_f32_16x16x32_bf16 v[6:9], v[150:153], v[214:217], v[6:9]
	v_mfma_f32_16x16x32_bf16 v[2:5], v[164:167], v[214:217], v[2:5]
	s_setprio 0
	s_barrier
	s_add_i32 s6, 0, 0x18000
	s_add_i32 s7, 0, 0x1c000
	v_add_u32_e32 v142, s6, v179
	v_add_u32_e32 v164, s7, v179
	ds_read_b128 v[130:133], v142
	ds_read_b128 v[134:137], v142 offset:1024
	ds_read_b128 v[138:141], v142 offset:2048
	ds_read_b128 v[142:145], v142 offset:3072
	ds_read_b128 v[146:149], v164
	ds_read_b128 v[150:153], v164 offset:1024
	ds_read_b128 v[154:157], v164 offset:2048
	ds_read_b128 v[164:167], v164 offset:3072
	s_add_u32 s20, s60, 0x160000
	s_addc_u32 s21, s61, 0
	s_mov_b32 m0, s22
	ds_read_b128 v[168:171], v181 offset:32768
	ds_read_b128 v[172:175], v181 offset:33792
	ds_read_b128 v[182:185], v181 offset:34816
	ds_read_b128 v[186:189], v181 offset:35840
	ds_read_b128 v[190:193], v181 offset:36864
	ds_read_b128 v[200:203], v181 offset:37888
	ds_read_b128 v[204:207], v181 offset:38912
	ds_read_b128 v[214:217], v181 offset:39936
	global_load_lds_dwordx4 v0, s[20:21]
	s_mov_b32 m0, s23
	s_nop 0
	global_load_lds_dwordx4 v158, s[20:21]
	s_waitcnt vmcnt(8)
	s_waitcnt lgkmcnt(0)
	s_barrier
	s_setprio 1
	s_waitcnt lgkmcnt(0)
	v_mfma_f32_16x16x32_bf16 v[126:129], v[130:133], v[168:171], v[126:129]
	v_mfma_f32_16x16x32_bf16 v[122:125], v[138:141], v[168:171], v[122:125]
	v_mfma_f32_16x16x32_bf16 v[110:113], v[130:133], v[182:185], v[110:113]
	v_mfma_f32_16x16x32_bf16 v[106:109], v[138:141], v[182:185], v[106:109]
	v_mfma_f32_16x16x32_bf16 v[94:97], v[130:133], v[190:193], v[94:97]
	v_mfma_f32_16x16x32_bf16 v[90:93], v[138:141], v[190:193], v[90:93]
	v_mfma_f32_16x16x32_bf16 v[78:81], v[130:133], v[204:207], v[78:81]
	v_mfma_f32_16x16x32_bf16 v[74:77], v[138:141], v[204:207], v[74:77]
	v_mfma_f32_16x16x32_bf16 v[126:129], v[134:137], v[172:175], v[126:129]
	v_mfma_f32_16x16x32_bf16 v[122:125], v[142:145], v[172:175], v[122:125]
	v_mfma_f32_16x16x32_bf16 v[110:113], v[134:137], v[186:189], v[110:113]
	v_mfma_f32_16x16x32_bf16 v[106:109], v[142:145], v[186:189], v[106:109]
	v_mfma_f32_16x16x32_bf16 v[94:97], v[134:137], v[200:203], v[94:97]
	v_mfma_f32_16x16x32_bf16 v[90:93], v[142:145], v[200:203], v[90:93]
	v_mfma_f32_16x16x32_bf16 v[78:81], v[134:137], v[214:217], v[78:81]
	v_mfma_f32_16x16x32_bf16 v[74:77], v[142:145], v[214:217], v[74:77]
	s_setprio 0
	s_setprio 1
	v_mfma_f32_16x16x32_bf16 v[118:121], v[146:149], v[168:171], v[118:121]
	v_mfma_f32_16x16x32_bf16 v[114:117], v[154:157], v[168:171], v[114:117]
	v_mfma_f32_16x16x32_bf16 v[102:105], v[146:149], v[182:185], v[102:105]
	v_mfma_f32_16x16x32_bf16 v[98:101], v[154:157], v[182:185], v[98:101]
	v_mfma_f32_16x16x32_bf16 v[86:89], v[146:149], v[190:193], v[86:89]
	v_mfma_f32_16x16x32_bf16 v[82:85], v[154:157], v[190:193], v[82:85]
	v_mfma_f32_16x16x32_bf16 v[70:73], v[146:149], v[204:207], v[70:73]
	v_mfma_f32_16x16x32_bf16 v[66:69], v[154:157], v[204:207], v[66:69]
	v_mfma_f32_16x16x32_bf16 v[118:121], v[150:153], v[172:175], v[118:121]
	v_mfma_f32_16x16x32_bf16 v[114:117], v[164:167], v[172:175], v[114:117]
	v_mfma_f32_16x16x32_bf16 v[102:105], v[150:153], v[186:189], v[102:105]
	v_mfma_f32_16x16x32_bf16 v[98:101], v[164:167], v[186:189], v[98:101]
	v_mfma_f32_16x16x32_bf16 v[86:89], v[150:153], v[200:203], v[86:89]
	v_mfma_f32_16x16x32_bf16 v[82:85], v[164:167], v[200:203], v[82:85]
	v_mfma_f32_16x16x32_bf16 v[70:73], v[150:153], v[214:217], v[70:73]
	v_mfma_f32_16x16x32_bf16 v[66:69], v[164:167], v[214:217], v[66:69]
	s_setprio 0
	s_barrier
	s_add_i32 s6, s6, s29
	s_mov_b32 m0, s6
	ds_read_b128 v[168:171], v181 offset:49152
	ds_read_b128 v[172:175], v181 offset:50176
	ds_read_b128 v[182:185], v181 offset:51200
	ds_read_b128 v[186:189], v181 offset:52224
	ds_read_b128 v[190:193], v181 offset:53248
	ds_read_b128 v[200:203], v181 offset:54272
	ds_read_b128 v[204:207], v181 offset:55296
	ds_read_b128 v[214:217], v181 offset:56320
	s_add_u32 s100, s58, s72
	s_addc_u32 s101, s59, s73
	global_load_lds_dwordx4 v0, s[100:101]
	s_add_i32 m0, s6, 0x2000
	s_add_u32 s20, s58, 0x160080
	s_addc_u32 s21, s59, 0
	s_add_i32 s6, s7, s29
	global_load_lds_dwordx4 v158, s[100:101]
	s_mov_b32 m0, s6
	s_nop 0
	global_load_lds_dwordx4 v0, s[20:21]
	s_add_i32 m0, s6, 0x2000
	s_nop 0
	global_load_lds_dwordx4 v158, s[20:21]
	s_mov_b32 m0, s8
	s_nop 0
	s_add_u32 s100, s60, s72
	s_addc_u32 s101, s61, s73
	global_load_lds_dwordx4 v0, s[100:101]
	s_mov_b32 m0, s9
	s_nop 0
	global_load_lds_dwordx4 v158, s[100:101]
	s_waitcnt vmcnt(8)
	s_waitcnt lgkmcnt(0)
	s_barrier
	s_setprio 1
	s_waitcnt lgkmcnt(0)
	v_mfma_f32_16x16x32_bf16 v[62:65], v[130:133], v[168:171], v[62:65]
	v_mfma_f32_16x16x32_bf16 v[58:61], v[138:141], v[168:171], v[58:61]
	v_mfma_f32_16x16x32_bf16 v[46:49], v[130:133], v[182:185], v[46:49]
	v_mfma_f32_16x16x32_bf16 v[42:45], v[138:141], v[182:185], v[42:45]
	v_mfma_f32_16x16x32_bf16 v[30:33], v[130:133], v[190:193], v[30:33]
	v_mfma_f32_16x16x32_bf16 v[26:29], v[138:141], v[190:193], v[26:29]
	v_mfma_f32_16x16x32_bf16 v[14:17], v[130:133], v[204:207], v[14:17]
	v_mfma_f32_16x16x32_bf16 v[10:13], v[138:141], v[204:207], v[10:13]
	v_mfma_f32_16x16x32_bf16 v[62:65], v[134:137], v[172:175], v[62:65]
	v_mfma_f32_16x16x32_bf16 v[58:61], v[142:145], v[172:175], v[58:61]
	v_mfma_f32_16x16x32_bf16 v[46:49], v[134:137], v[186:189], v[46:49]
	v_mfma_f32_16x16x32_bf16 v[42:45], v[142:145], v[186:189], v[42:45]
	v_mfma_f32_16x16x32_bf16 v[30:33], v[134:137], v[200:203], v[30:33]
	v_mfma_f32_16x16x32_bf16 v[26:29], v[142:145], v[200:203], v[26:29]
	v_mfma_f32_16x16x32_bf16 v[14:17], v[134:137], v[214:217], v[14:17]
	v_mfma_f32_16x16x32_bf16 v[10:13], v[142:145], v[214:217], v[10:13]
	s_setprio 0
	s_setprio 1
	v_mfma_f32_16x16x32_bf16 v[54:57], v[146:149], v[168:171], v[54:57]
	v_mfma_f32_16x16x32_bf16 v[50:53], v[154:157], v[168:171], v[50:53]
	v_mfma_f32_16x16x32_bf16 v[38:41], v[146:149], v[182:185], v[38:41]
	v_mfma_f32_16x16x32_bf16 v[34:37], v[154:157], v[182:185], v[34:37]
	v_mfma_f32_16x16x32_bf16 v[22:25], v[146:149], v[190:193], v[22:25]
	v_mfma_f32_16x16x32_bf16 v[18:21], v[154:157], v[190:193], v[18:21]
	v_mfma_f32_16x16x32_bf16 v[6:9], v[146:149], v[204:207], v[6:9]
	v_mfma_f32_16x16x32_bf16 v[2:5], v[154:157], v[204:207], v[2:5]
	v_mfma_f32_16x16x32_bf16 v[54:57], v[150:153], v[172:175], v[54:57]
	v_mfma_f32_16x16x32_bf16 v[50:53], v[164:167], v[172:175], v[50:53]
	v_mfma_f32_16x16x32_bf16 v[38:41], v[150:153], v[186:189], v[38:41]
	v_mfma_f32_16x16x32_bf16 v[34:37], v[164:167], v[186:189], v[34:37]
	v_mfma_f32_16x16x32_bf16 v[22:25], v[150:153], v[200:203], v[22:25]
	v_mfma_f32_16x16x32_bf16 v[18:21], v[164:167], v[200:203], v[18:21]
	v_mfma_f32_16x16x32_bf16 v[6:9], v[150:153], v[214:217], v[6:9]
	v_mfma_f32_16x16x32_bf16 v[2:5], v[164:167], v[214:217], v[2:5]
	s_setprio 0
	s_barrier
	s_add_i32 s13, s13, 2
	s_add_u32 s11, s11, 0x100
	s_addc_u32 s12, s12, 0
	s_cmpk_gt_u32 s13, 0x55
	s_mov_b64 s[56:57], s[44:45]
	s_cbranch_scc0 .LBB0_586
	s_and_b64 vcc, exec, s[46:47]
	s_cbranch_vccz .LBB0_589
	s_barrier
